# plus: residual-GEMM epilogue with hoisted loads and counted waits
# speedup vs baseline: 1.0451x; 1.0058x over previous
;     __device__ __forceinline__ void operator()(const f32x4 (&acc)[2][2][4][2], const pg8::Unit& u, int wr, int wc, int fr, int fq) const {
;     ...
;         const int row0 = rowt + wr * 64 + fr, col0 = u.pn * 256 + wc * 32 + 8 * fq;
;         const float* gp = gate + (size_t)grp * (NMOD * DM) + col0;
;         float sq[2][4];
; #pragma unroll
;         for (int ai = 0; ai < 2; ++ai)
; #pragma unroll
;             for (int m = 0; m < 4; ++m) sq[ai][m] = 0.f;
; #pragma unroll
;         for (int bj = 0; bj < 2; ++bj) {
;             const f32x4 g0 = *(const f32x4*)(gp + bj * 128) * coef, g1 = *(const f32x4*)(gp + bj * 128 + 4) * coef;
;             f32x4 s0, s1, i0, i1;
;             { const float* np_ = ngn + col0 + bj * 128; const float* sp_ = scn + (size_t)grp * (NMOD * DM) + col0 + bj * 128;
;                 s0 = *(const f32x4*)np_ * (*(const f32x4*)sp_ + 1.f); s1 = *(const f32x4*)(np_ + 4) * (*(const f32x4*)(sp_ + 4) + 1.f);
;                 const float* pp_ = ngp + col0 + bj * 128; const float* qp_ = scp + (size_t)grp * (NMOD * DM) + col0 + bj * 128;
;                 const f32x4 p0 = *(const f32x4*)pp_ * (*(const f32x4*)qp_ + 1.f), p1 = *(const f32x4*)(pp_ + 4) * (*(const f32x4*)(qp_ + 4) + 1.f);
;                 i0 = (f32x4){rcpf_(p0[0]), rcpf_(p0[1]), rcpf_(p0[2]), rcpf_(p0[3])}; i1 = (f32x4){rcpf_(p1[0]), rcpf_(p1[1]), rcpf_(p1[2]), rcpf_(p1[3])}; }
; #pragma unroll
;             for (int ai = 0; ai < 2; ++ai) {
;                 u32x4 rr[4];
; #pragma unroll
;                 for (int m = 0; m < 4; ++m) rr[m] = *(const u32x4*)(Un + (size_t)(row0 + ai * 128 + m * 16) * DM + col0 + bj * 128);
;                 __builtin_amdgcn_sched_barrier(0);
; #pragma unroll
;                 for (int m = 0; m < 4; ++m) {
;                     const size_t off = (size_t)(row0 + ai * 128 + m * 16) * DM + col0 + bj * 128;
;                     const u32x4 r = rr[m];
;                     f32x4 h0 = (f32x4){bf2f(r.x & 0xffffu), __builtin_bit_cast(float, r.x & 0xffff0000u), bf2f(r.y & 0xffffu), __builtin_bit_cast(float, r.y & 0xffff0000u)};
;                     f32x4 h1 = (f32x4){bf2f(r.z & 0xffffu), __builtin_bit_cast(float, r.z & 0xffff0000u), bf2f(r.w & 0xffffu), __builtin_bit_cast(float, r.w & 0xffff0000u)};
;                     h0 = h0 * i0 + g0 * acc[ai][bj][m][0]; h1 = h1 * i1 + g1 * acc[ai][bj][m][1];
.LBB0_316:
	s_ashr_i32 s1, s66, 6
	s_lshl_b32 s24, s46, 8
	s_or_b32 s33, s24, s48
	s_add_i32 s58, s17, s47
	s_mul_hi_i32 s25, s1, 0x9000
	s_mul_i32 s1, s1, 0x9000
	s_add_u32 s26, s49, s1
	s_addc_u32 s27, s50, s25
	s_add_u32 s66, s45, s1
	s_addc_u32 s67, s44, s25
	s_add_u32 s24, s51, s1
	s_addc_u32 s25, s52, s25
	v_readlane_b32 s0, v253, 48
	v_readlane_b32 s1, v253, 49
	s_waitcnt lgkmcnt(0)
	v_lshl_add_u32 v143, v235, 3, s33
	v_add_u32_e32 v163, s58, v234
	v_lshlrev_b32_e32 v154, 2, v143
	v_lshlrev_b32_e32 v222, 1, v143
	v_lshl_add_u32 v155, v163, 11, v222
	v_add_u32_e32 v156, 0x8000, v155
	v_add_u32_e32 v157, 0x10000, v155
	v_add_u32_e32 v158, 0x18000, v155
	v_add_u32_e32 v159, 0x40000, v155
	v_add_u32_e32 v160, 0x48000, v155
	v_add_u32_e32 v161, 0x50000, v155
	v_add_u32_e32 v162, 0x58000, v155
	global_load_dwordx4 v[172:175], v154, s[26:27]
	global_load_dwordx4 v[176:179], v154, s[26:27] offset:16
	global_load_dwordx4 v[180:183], v154, s[6:7]
	global_load_dwordx4 v[184:187], v154, s[6:7] offset:16
	global_load_dwordx4 v[188:191], v154, s[66:67]
	global_load_dwordx4 v[192:195], v154, s[66:67] offset:16
	global_load_dwordx4 v[196:199], v154, s[10:11]
	global_load_dwordx4 v[200:203], v154, s[10:11] offset:16
	global_load_dwordx4 v[204:207], v154, s[24:25]
	global_load_dwordx4 v[208:211], v154, s[24:25] offset:16
	global_load_dwordx4 v[212:215], v155, s[0:1]
	global_load_dwordx4 v[216:219], v156, s[0:1]
	global_load_dwordx4 v[236:239], v157, s[0:1]
	global_load_dwordx4 v[240:243], v158, s[0:1]
	global_load_dwordx4 v[244:247], v159, s[0:1]
	global_load_dwordx4 v[248:251], v160, s[0:1]
	global_load_dwordx4 v[128:131], v161, s[0:1]
	global_load_dwordx4 v[132:135], v162, s[0:1]
	s_waitcnt vmcnt(8)
	v_pk_mul_f32 v[172:173], v[148:149], v[172:173]
	v_pk_mul_f32 v[174:175], v[148:149], v[174:175]
	v_pk_mul_f32 v[176:177], v[148:149], v[176:177]
	v_pk_mul_f32 v[178:179], v[148:149], v[178:179]
	v_pk_add_f32 v[188:189], v[188:189], 1.0 op_sel_hi:[1,0]
	v_pk_add_f32 v[190:191], v[190:191], 1.0 op_sel_hi:[1,0]
	v_pk_add_f32 v[192:193], v[192:193], 1.0 op_sel_hi:[1,0]
	v_pk_add_f32 v[194:195], v[194:195], 1.0 op_sel_hi:[1,0]
	v_pk_add_f32 v[204:205], v[204:205], 1.0 op_sel_hi:[1,0]
	v_pk_add_f32 v[206:207], v[206:207], 1.0 op_sel_hi:[1,0]
	v_pk_add_f32 v[208:209], v[208:209], 1.0 op_sel_hi:[1,0]
	v_pk_add_f32 v[210:211], v[210:211], 1.0 op_sel_hi:[1,0]
	v_pk_mul_f32 v[180:181], v[180:181], v[188:189]
	v_pk_mul_f32 v[182:183], v[182:183], v[190:191]
	v_pk_mul_f32 v[184:185], v[184:185], v[192:193]
	v_pk_mul_f32 v[186:187], v[186:187], v[194:195]
	v_pk_mul_f32 v[196:197], v[196:197], v[204:205]
	v_pk_mul_f32 v[198:199], v[198:199], v[206:207]
	v_pk_mul_f32 v[200:201], v[200:201], v[208:209]
	v_pk_mul_f32 v[202:203], v[202:203], v[210:211]
	v_rcp_f32_e32 v196, v196
	v_rcp_f32_e32 v197, v197
	v_rcp_f32_e32 v198, v198
	v_rcp_f32_e32 v199, v199
	v_rcp_f32_e32 v200, v200
	v_rcp_f32_e32 v201, v201
	v_rcp_f32_e32 v202, v202
	v_rcp_f32_e32 v203, v203
	s_nop 0
	s_waitcnt vmcnt(4)
	v_lshlrev_b32_e32 v188, 16, v212
	v_and_b32_e32 v189, 0xffff0000, v212
	v_lshlrev_b32_e32 v190, 16, v213
	v_and_b32_e32 v191, 0xffff0000, v213
	v_lshlrev_b32_e32 v192, 16, v214
	v_and_b32_e32 v193, 0xffff0000, v214
	v_lshlrev_b32_e32 v194, 16, v215
	v_and_b32_e32 v195, 0xffff0000, v215
	v_pk_mul_f32 v[188:189], v[196:197], v[188:189]
	v_pk_mul_f32 v[190:191], v[198:199], v[190:191]
	v_pk_mul_f32 v[192:193], v[200:201], v[192:193]
	v_pk_mul_f32 v[194:195], v[202:203], v[194:195]
	v_pk_fma_f32 v[188:189], v[124:125], v[172:173], v[188:189]
	v_pk_fma_f32 v[190:191], v[126:127], v[174:175], v[190:191]
	v_pk_fma_f32 v[192:193], v[120:121], v[176:177], v[192:193]
	v_pk_fma_f32 v[194:195], v[122:123], v[178:179], v[194:195]
	v_mul_f32_e32 v222, v189, v189
	v_mul_f32_e32 v223, v191, v191
	v_fmac_f32_e32 v222, v188, v188
	v_fmac_f32_e32 v223, v190, v190
	v_add_f32_e32 v222, v222, v223
	v_mul_f32_e32 v223, v193, v193
	v_mul_f32_e32 v228, v195, v195
	v_fmac_f32_e32 v223, v192, v192
	v_fmac_f32_e32 v228, v194, v194
	v_add_f32_e32 v223, v223, v228
	v_add_f32_e32 v164, v222, v223
	v_pk_mul_f32 v[188:189], v[180:181], v[188:189]
	v_pk_mul_f32 v[190:191], v[182:183], v[190:191]
	v_pk_mul_f32 v[192:193], v[184:185], v[192:193]
	v_pk_mul_f32 v[194:195], v[186:187], v[194:195]
	v_cvt_pk_bf16_f32 v212, v188, v189
	v_cvt_pk_bf16_f32 v213, v190, v191
	v_cvt_pk_bf16_f32 v214, v192, v193
	v_cvt_pk_bf16_f32 v215, v194, v195
	global_store_dwordx4 v155, v[212:215], s[0:1]
	v_lshlrev_b32_e32 v188, 16, v216
	v_and_b32_e32 v189, 0xffff0000, v216
	v_lshlrev_b32_e32 v190, 16, v217
	v_and_b32_e32 v191, 0xffff0000, v217
	v_lshlrev_b32_e32 v192, 16, v218
	v_and_b32_e32 v193, 0xffff0000, v218
	v_lshlrev_b32_e32 v194, 16, v219
	v_and_b32_e32 v195, 0xffff0000, v219
	v_pk_mul_f32 v[188:189], v[196:197], v[188:189]
	v_pk_mul_f32 v[190:191], v[198:199], v[190:191]
	v_pk_mul_f32 v[192:193], v[200:201], v[192:193]
	v_pk_mul_f32 v[194:195], v[202:203], v[194:195]
	v_pk_fma_f32 v[188:189], v[116:117], v[172:173], v[188:189]
	v_pk_fma_f32 v[190:191], v[118:119], v[174:175], v[190:191]
	v_pk_fma_f32 v[192:193], v[112:113], v[176:177], v[192:193]
	v_pk_fma_f32 v[194:195], v[114:115], v[178:179], v[194:195]
	v_mul_f32_e32 v222, v189, v189
	v_mul_f32_e32 v223, v191, v191
	v_fmac_f32_e32 v222, v188, v188
	v_fmac_f32_e32 v223, v190, v190
	v_add_f32_e32 v222, v222, v223
	v_mul_f32_e32 v223, v193, v193
	v_mul_f32_e32 v228, v195, v195
	v_fmac_f32_e32 v223, v192, v192
	v_fmac_f32_e32 v228, v194, v194
	v_add_f32_e32 v223, v223, v228
	v_add_f32_e32 v165, v222, v223
	v_pk_mul_f32 v[188:189], v[180:181], v[188:189]
	v_pk_mul_f32 v[190:191], v[182:183], v[190:191]
;     __device__ __forceinline__ void operator()(const f32x4 (&acc)[2][2][4][2], const pg8::Unit& u, int wr, int wc, int fr, int fq) const {
;     ...
;             const f32x4 g0 = *(const f32x4*)(gp + bj * 128) * coef, g1 = *(const f32x4*)(gp + bj * 128 + 4) * coef;
;             f32x4 s0, s1, i0, i1;
;             { const float* np_ = ngn + col0 + bj * 128; const float* sp_ = scn + (size_t)grp * (NMOD * DM) + col0 + bj * 128;
;                 s0 = *(const f32x4*)np_ * (*(const f32x4*)sp_ + 1.f); s1 = *(const f32x4*)(np_ + 4) * (*(const f32x4*)(sp_ + 4) + 1.f);
;                 const float* pp_ = ngp + col0 + bj * 128; const float* qp_ = scp + (size_t)grp * (NMOD * DM) + col0 + bj * 128;
;                 const f32x4 p0 = *(const f32x4*)pp_ * (*(const f32x4*)qp_ + 1.f), p1 = *(const f32x4*)(pp_ + 4) * (*(const f32x4*)(qp_ + 4) + 1.f);
;                 i0 = (f32x4){rcpf_(p0[0]), rcpf_(p0[1]), rcpf_(p0[2]), rcpf_(p0[3])}; i1 = (f32x4){rcpf_(p1[0]), rcpf_(p1[1]), rcpf_(p1[2]), rcpf_(p1[3])}; }
; #pragma unroll
;             for (int ai = 0; ai < 2; ++ai) {
;                 u32x4 rr[4];
; #pragma unroll
;                 for (int m = 0; m < 4; ++m) rr[m] = *(const u32x4*)(Un + (size_t)(row0 + ai * 128 + m * 16) * DM + col0 + bj * 128);
;                 __builtin_amdgcn_sched_barrier(0);
; #pragma unroll
;                 for (int m = 0; m < 4; ++m) {
;                     const size_t off = (size_t)(row0 + ai * 128 + m * 16) * DM + col0 + bj * 128;
;                     const u32x4 r = rr[m];
;                     f32x4 h0 = (f32x4){bf2f(r.x & 0xffffu), __builtin_bit_cast(float, r.x & 0xffff0000u), bf2f(r.y & 0xffffu), __builtin_bit_cast(float, r.y & 0xffff0000u)};
;                     f32x4 h1 = (f32x4){bf2f(r.z & 0xffffu), __builtin_bit_cast(float, r.z & 0xffff0000u), bf2f(r.w & 0xffffu), __builtin_bit_cast(float, r.w & 0xffff0000u)};
;                     h0 = h0 * i0 + g0 * acc[ai][bj][m][0]; h1 = h1 * i1 + g1 * acc[ai][bj][m][1];
;                     sq[ai][m] += ((h0[0] * h0[0] + h0[1] * h0[1]) + (h0[2] * h0[2] + h0[3] * h0[3])) + ((h1[0] * h1[0] + h1[1] * h1[1]) + (h1[2] * h1[2] + h1[3] * h1[3]));
;                     asm volatile("" : "+v"(sq[ai][m]));
;                     const f32x4 u0 = h0 * s0, u1 = h1 * s1;
;                     u32x4 w; w.x = pk2(u0[0], u0[1]); w.y = pk2(u0[2], u0[3]); w.z = pk2(u1[0], u1[1]); w.w = pk2(u1[2], u1[3]);
	v_pk_mul_f32 v[192:193], v[184:185], v[192:193]
	v_pk_mul_f32 v[194:195], v[186:187], v[194:195]
	v_cvt_pk_bf16_f32 v216, v188, v189
	v_cvt_pk_bf16_f32 v217, v190, v191
	v_cvt_pk_bf16_f32 v218, v192, v193
	v_cvt_pk_bf16_f32 v219, v194, v195
	global_store_dwordx4 v156, v[216:219], s[0:1]
	v_lshlrev_b32_e32 v188, 16, v236
	v_and_b32_e32 v189, 0xffff0000, v236
	v_lshlrev_b32_e32 v190, 16, v237
	v_and_b32_e32 v191, 0xffff0000, v237
	v_lshlrev_b32_e32 v192, 16, v238
	v_and_b32_e32 v193, 0xffff0000, v238
	v_lshlrev_b32_e32 v194, 16, v239
	v_and_b32_e32 v195, 0xffff0000, v239
	v_pk_mul_f32 v[188:189], v[196:197], v[188:189]
	v_pk_mul_f32 v[190:191], v[198:199], v[190:191]
	v_pk_mul_f32 v[192:193], v[200:201], v[192:193]
	v_pk_mul_f32 v[194:195], v[202:203], v[194:195]
	v_pk_fma_f32 v[188:189], v[108:109], v[172:173], v[188:189]
	v_pk_fma_f32 v[190:191], v[110:111], v[174:175], v[190:191]
	v_pk_fma_f32 v[192:193], v[104:105], v[176:177], v[192:193]
	v_pk_fma_f32 v[194:195], v[106:107], v[178:179], v[194:195]
	v_mul_f32_e32 v222, v189, v189
	v_mul_f32_e32 v223, v191, v191
	v_fmac_f32_e32 v222, v188, v188
	v_fmac_f32_e32 v223, v190, v190
	v_add_f32_e32 v222, v222, v223
	v_mul_f32_e32 v223, v193, v193
	v_mul_f32_e32 v228, v195, v195
	v_fmac_f32_e32 v223, v192, v192
	v_fmac_f32_e32 v228, v194, v194
	v_add_f32_e32 v223, v223, v228
	v_add_f32_e32 v166, v222, v223
	v_pk_mul_f32 v[188:189], v[180:181], v[188:189]
	v_pk_mul_f32 v[190:191], v[182:183], v[190:191]
	v_pk_mul_f32 v[192:193], v[184:185], v[192:193]
	v_pk_mul_f32 v[194:195], v[186:187], v[194:195]
	v_cvt_pk_bf16_f32 v236, v188, v189
	v_cvt_pk_bf16_f32 v237, v190, v191
	v_cvt_pk_bf16_f32 v238, v192, v193
	v_cvt_pk_bf16_f32 v239, v194, v195
	global_store_dwordx4 v157, v[236:239], s[0:1]
	v_lshlrev_b32_e32 v188, 16, v240
	v_and_b32_e32 v189, 0xffff0000, v240
	v_lshlrev_b32_e32 v190, 16, v241
	v_and_b32_e32 v191, 0xffff0000, v241
	v_lshlrev_b32_e32 v192, 16, v242
	v_and_b32_e32 v193, 0xffff0000, v242
	v_lshlrev_b32_e32 v194, 16, v243
	v_and_b32_e32 v195, 0xffff0000, v243
	v_pk_mul_f32 v[188:189], v[196:197], v[188:189]
	v_pk_mul_f32 v[190:191], v[198:199], v[190:191]
	v_pk_mul_f32 v[192:193], v[200:201], v[192:193]
	v_pk_mul_f32 v[194:195], v[202:203], v[194:195]
	v_pk_fma_f32 v[188:189], v[100:101], v[172:173], v[188:189]
	v_pk_fma_f32 v[190:191], v[102:103], v[174:175], v[190:191]
	v_pk_fma_f32 v[192:193], v[96:97], v[176:177], v[192:193]
	v_pk_fma_f32 v[194:195], v[98:99], v[178:179], v[194:195]
	v_mul_f32_e32 v222, v189, v189
	v_mul_f32_e32 v223, v191, v191
	v_fmac_f32_e32 v222, v188, v188
	v_fmac_f32_e32 v223, v190, v190
	v_add_f32_e32 v222, v222, v223
	v_mul_f32_e32 v223, v193, v193
	v_mul_f32_e32 v228, v195, v195
	v_fmac_f32_e32 v223, v192, v192
	v_fmac_f32_e32 v228, v194, v194
	v_add_f32_e32 v223, v223, v228
	v_add_f32_e32 v167, v222, v223
	v_pk_mul_f32 v[188:189], v[180:181], v[188:189]
	v_pk_mul_f32 v[190:191], v[182:183], v[190:191]
	v_pk_mul_f32 v[192:193], v[184:185], v[192:193]
	v_pk_mul_f32 v[194:195], v[186:187], v[194:195]
	v_cvt_pk_bf16_f32 v240, v188, v189
	v_cvt_pk_bf16_f32 v241, v190, v191
	v_cvt_pk_bf16_f32 v242, v192, v193
	v_cvt_pk_bf16_f32 v243, v194, v195
	global_store_dwordx4 v158, v[240:243], s[0:1]
	global_load_dwordx4 v[96:99], v154, s[26:27] offset:512
	global_load_dwordx4 v[100:103], v154, s[26:27] offset:528
	global_load_dwordx4 v[104:107], v154, s[6:7] offset:512
	global_load_dwordx4 v[108:111], v154, s[6:7] offset:528
	global_load_dwordx4 v[112:115], v154, s[66:67] offset:512
	global_load_dwordx4 v[116:119], v154, s[66:67] offset:528
	global_load_dwordx4 v[120:123], v154, s[10:11] offset:512
	global_load_dwordx4 v[124:127], v154, s[10:11] offset:528
	global_load_dwordx4 v[212:215], v154, s[24:25] offset:512
	global_load_dwordx4 v[216:219], v154, s[24:25] offset:528
	global_load_dwordx4 v[236:239], v155, s[0:1] offset:256
	global_load_dwordx4 v[240:243], v156, s[0:1] offset:256
	global_load_dwordx4 v[204:207], v157, s[0:1] offset:256
	global_load_dwordx4 v[208:211], v158, s[0:1] offset:256
	s_waitcnt vmcnt(18)
	v_lshlrev_b32_e32 v188, 16, v244
	v_and_b32_e32 v189, 0xffff0000, v244
	v_lshlrev_b32_e32 v190, 16, v245
	v_and_b32_e32 v191, 0xffff0000, v245
	v_lshlrev_b32_e32 v192, 16, v246
	v_and_b32_e32 v193, 0xffff0000, v246
	v_lshlrev_b32_e32 v194, 16, v247
	v_and_b32_e32 v195, 0xffff0000, v247
	v_pk_mul_f32 v[188:189], v[196:197], v[188:189]
	v_pk_mul_f32 v[190:191], v[198:199], v[190:191]
	v_pk_mul_f32 v[192:193], v[200:201], v[192:193]
	v_pk_mul_f32 v[194:195], v[202:203], v[194:195]
	v_pk_fma_f32 v[188:189], v[92:93], v[172:173], v[188:189]
	v_pk_fma_f32 v[190:191], v[94:95], v[174:175], v[190:191]
	v_pk_fma_f32 v[192:193], v[88:89], v[176:177], v[192:193]
	v_pk_fma_f32 v[194:195], v[90:91], v[178:179], v[194:195]
	v_mul_f32_e32 v222, v189, v189
	v_mul_f32_e32 v223, v191, v191
	v_fmac_f32_e32 v222, v188, v188
	v_fmac_f32_e32 v223, v190, v190
	v_add_f32_e32 v222, v222, v223
	v_mul_f32_e32 v223, v193, v193
	v_mul_f32_e32 v228, v195, v195
	v_fmac_f32_e32 v223, v192, v192
	v_fmac_f32_e32 v228, v194, v194
	v_add_f32_e32 v223, v223, v228
	v_add_f32_e32 v168, v222, v223
	v_pk_mul_f32 v[188:189], v[180:181], v[188:189]
	v_pk_mul_f32 v[190:191], v[182:183], v[190:191]
	v_pk_mul_f32 v[192:193], v[184:185], v[192:193]
	v_pk_mul_f32 v[194:195], v[186:187], v[194:195]
	v_cvt_pk_bf16_f32 v244, v188, v189
	v_cvt_pk_bf16_f32 v245, v190, v191
	v_cvt_pk_bf16_f32 v246, v192, v193
	v_cvt_pk_bf16_f32 v247, v194, v195
	global_store_dwordx4 v159, v[244:247], s[0:1]
	v_lshlrev_b32_e32 v188, 16, v248
	v_and_b32_e32 v189, 0xffff0000, v248
	v_lshlrev_b32_e32 v190, 16, v249
;     __device__ __forceinline__ void operator()(const f32x4 (&acc)[2][2][4][2], const pg8::Unit& u, int wr, int wc, int fr, int fq) const {
;     ...
;             const f32x4 g0 = *(const f32x4*)(gp + bj * 128) * coef, g1 = *(const f32x4*)(gp + bj * 128 + 4) * coef;
;             f32x4 s0, s1, i0, i1;
;             { const float* np_ = ngn + col0 + bj * 128; const float* sp_ = scn + (size_t)grp * (NMOD * DM) + col0 + bj * 128;
;                 s0 = *(const f32x4*)np_ * (*(const f32x4*)sp_ + 1.f); s1 = *(const f32x4*)(np_ + 4) * (*(const f32x4*)(sp_ + 4) + 1.f);
;                 const float* pp_ = ngp + col0 + bj * 128; const float* qp_ = scp + (size_t)grp * (NMOD * DM) + col0 + bj * 128;
;                 const f32x4 p0 = *(const f32x4*)pp_ * (*(const f32x4*)qp_ + 1.f), p1 = *(const f32x4*)(pp_ + 4) * (*(const f32x4*)(qp_ + 4) + 1.f);
;                 i0 = (f32x4){rcpf_(p0[0]), rcpf_(p0[1]), rcpf_(p0[2]), rcpf_(p0[3])}; i1 = (f32x4){rcpf_(p1[0]), rcpf_(p1[1]), rcpf_(p1[2]), rcpf_(p1[3])}; }
; #pragma unroll
;             for (int ai = 0; ai < 2; ++ai) {
;                 u32x4 rr[4];
; #pragma unroll
;                 for (int m = 0; m < 4; ++m) rr[m] = *(const u32x4*)(Un + (size_t)(row0 + ai * 128 + m * 16) * DM + col0 + bj * 128);
;                 __builtin_amdgcn_sched_barrier(0);
; #pragma unroll
;                 for (int m = 0; m < 4; ++m) {
;                     const size_t off = (size_t)(row0 + ai * 128 + m * 16) * DM + col0 + bj * 128;
;                     const u32x4 r = rr[m];
;                     f32x4 h0 = (f32x4){bf2f(r.x & 0xffffu), __builtin_bit_cast(float, r.x & 0xffff0000u), bf2f(r.y & 0xffffu), __builtin_bit_cast(float, r.y & 0xffff0000u)};
;                     f32x4 h1 = (f32x4){bf2f(r.z & 0xffffu), __builtin_bit_cast(float, r.z & 0xffff0000u), bf2f(r.w & 0xffffu), __builtin_bit_cast(float, r.w & 0xffff0000u)};
;                     h0 = h0 * i0 + g0 * acc[ai][bj][m][0]; h1 = h1 * i1 + g1 * acc[ai][bj][m][1];
;                     sq[ai][m] += ((h0[0] * h0[0] + h0[1] * h0[1]) + (h0[2] * h0[2] + h0[3] * h0[3])) + ((h1[0] * h1[0] + h1[1] * h1[1]) + (h1[2] * h1[2] + h1[3] * h1[3]));
;                     asm volatile("" : "+v"(sq[ai][m]));
;                     const f32x4 u0 = h0 * s0, u1 = h1 * s1;
;                     u32x4 w; w.x = pk2(u0[0], u0[1]); w.y = pk2(u0[2], u0[3]); w.z = pk2(u1[0], u1[1]); w.w = pk2(u1[2], u1[3]);
	v_and_b32_e32 v191, 0xffff0000, v249
	v_lshlrev_b32_e32 v192, 16, v250
	v_and_b32_e32 v193, 0xffff0000, v250
	v_lshlrev_b32_e32 v194, 16, v251
	v_and_b32_e32 v195, 0xffff0000, v251
	v_pk_mul_f32 v[188:189], v[196:197], v[188:189]
	v_pk_mul_f32 v[190:191], v[198:199], v[190:191]
	v_pk_mul_f32 v[192:193], v[200:201], v[192:193]
	v_pk_mul_f32 v[194:195], v[202:203], v[194:195]
	v_pk_fma_f32 v[188:189], v[84:85], v[172:173], v[188:189]
	v_pk_fma_f32 v[190:191], v[86:87], v[174:175], v[190:191]
	v_pk_fma_f32 v[192:193], v[80:81], v[176:177], v[192:193]
	v_pk_fma_f32 v[194:195], v[82:83], v[178:179], v[194:195]
	v_mul_f32_e32 v222, v189, v189
	v_mul_f32_e32 v223, v191, v191
	v_fmac_f32_e32 v222, v188, v188
	v_fmac_f32_e32 v223, v190, v190
	v_add_f32_e32 v222, v222, v223
	v_mul_f32_e32 v223, v193, v193
	v_mul_f32_e32 v228, v195, v195
	v_fmac_f32_e32 v223, v192, v192
	v_fmac_f32_e32 v228, v194, v194
	v_add_f32_e32 v223, v223, v228
	v_add_f32_e32 v169, v222, v223
	v_pk_mul_f32 v[188:189], v[180:181], v[188:189]
	v_pk_mul_f32 v[190:191], v[182:183], v[190:191]
	v_pk_mul_f32 v[192:193], v[184:185], v[192:193]
	v_pk_mul_f32 v[194:195], v[186:187], v[194:195]
	v_cvt_pk_bf16_f32 v248, v188, v189
	v_cvt_pk_bf16_f32 v249, v190, v191
	v_cvt_pk_bf16_f32 v250, v192, v193
	v_cvt_pk_bf16_f32 v251, v194, v195
	global_store_dwordx4 v160, v[248:251], s[0:1]
	v_lshlrev_b32_e32 v188, 16, v128
	v_and_b32_e32 v189, 0xffff0000, v128
	v_lshlrev_b32_e32 v190, 16, v129
	v_and_b32_e32 v191, 0xffff0000, v129
	v_lshlrev_b32_e32 v192, 16, v130
	v_and_b32_e32 v193, 0xffff0000, v130
	v_lshlrev_b32_e32 v194, 16, v131
	v_and_b32_e32 v195, 0xffff0000, v131
	v_pk_mul_f32 v[188:189], v[196:197], v[188:189]
	v_pk_mul_f32 v[190:191], v[198:199], v[190:191]
	v_pk_mul_f32 v[192:193], v[200:201], v[192:193]
	v_pk_mul_f32 v[194:195], v[202:203], v[194:195]
	v_pk_fma_f32 v[188:189], v[76:77], v[172:173], v[188:189]
	v_pk_fma_f32 v[190:191], v[78:79], v[174:175], v[190:191]
	v_pk_fma_f32 v[192:193], v[72:73], v[176:177], v[192:193]
	v_pk_fma_f32 v[194:195], v[74:75], v[178:179], v[194:195]
	v_mul_f32_e32 v222, v189, v189
	v_mul_f32_e32 v223, v191, v191
	v_fmac_f32_e32 v222, v188, v188
	v_fmac_f32_e32 v223, v190, v190
	v_add_f32_e32 v222, v222, v223
	v_mul_f32_e32 v223, v193, v193
	v_mul_f32_e32 v228, v195, v195
	v_fmac_f32_e32 v223, v192, v192
	v_fmac_f32_e32 v228, v194, v194
	v_add_f32_e32 v223, v223, v228
	v_add_f32_e32 v170, v222, v223
	v_pk_mul_f32 v[188:189], v[180:181], v[188:189]
	v_pk_mul_f32 v[190:191], v[182:183], v[190:191]
	v_pk_mul_f32 v[192:193], v[184:185], v[192:193]
	v_pk_mul_f32 v[194:195], v[186:187], v[194:195]
	v_cvt_pk_bf16_f32 v128, v188, v189
	v_cvt_pk_bf16_f32 v129, v190, v191
	v_cvt_pk_bf16_f32 v130, v192, v193
	v_cvt_pk_bf16_f32 v131, v194, v195
	global_store_dwordx4 v161, v[128:131], s[0:1]
	v_lshlrev_b32_e32 v188, 16, v132
	v_and_b32_e32 v189, 0xffff0000, v132
	v_lshlrev_b32_e32 v190, 16, v133
	v_and_b32_e32 v191, 0xffff0000, v133
	v_lshlrev_b32_e32 v192, 16, v134
	v_and_b32_e32 v193, 0xffff0000, v134
	v_lshlrev_b32_e32 v194, 16, v135
	v_and_b32_e32 v195, 0xffff0000, v135
	v_pk_mul_f32 v[188:189], v[196:197], v[188:189]
	v_pk_mul_f32 v[190:191], v[198:199], v[190:191]
	v_pk_mul_f32 v[192:193], v[200:201], v[192:193]
	v_pk_mul_f32 v[194:195], v[202:203], v[194:195]
	v_pk_fma_f32 v[188:189], v[68:69], v[172:173], v[188:189]
	v_pk_fma_f32 v[190:191], v[70:71], v[174:175], v[190:191]
	v_pk_fma_f32 v[192:193], v[64:65], v[176:177], v[192:193]
	v_pk_fma_f32 v[194:195], v[66:67], v[178:179], v[194:195]
	v_mul_f32_e32 v222, v189, v189
	v_mul_f32_e32 v223, v191, v191
	v_fmac_f32_e32 v222, v188, v188
	v_fmac_f32_e32 v223, v190, v190
	v_add_f32_e32 v222, v222, v223
	v_mul_f32_e32 v223, v193, v193
	v_mul_f32_e32 v228, v195, v195
	v_fmac_f32_e32 v223, v192, v192
	v_fmac_f32_e32 v228, v194, v194
	v_add_f32_e32 v223, v223, v228
	v_add_f32_e32 v171, v222, v223
	v_pk_mul_f32 v[188:189], v[180:181], v[188:189]
	v_pk_mul_f32 v[190:191], v[182:183], v[190:191]
	v_pk_mul_f32 v[192:193], v[184:185], v[192:193]
	v_pk_mul_f32 v[194:195], v[186:187], v[194:195]
	v_cvt_pk_bf16_f32 v132, v188, v189
	v_cvt_pk_bf16_f32 v133, v190, v191
	v_cvt_pk_bf16_f32 v134, v192, v193
	v_cvt_pk_bf16_f32 v135, v194, v195
	global_store_dwordx4 v162, v[132:135], s[0:1]
	s_nop 1
	global_load_dwordx4 v[244:247], v159, s[0:1] offset:256
	global_load_dwordx4 v[248:251], v160, s[0:1] offset:256
	global_load_dwordx4 v[128:131], v161, s[0:1] offset:256
	global_load_dwordx4 v[132:135], v162, s[0:1] offset:256
	s_waitcnt vmcnt(12)
	v_pk_mul_f32 v[96:97], v[148:149], v[96:97]
	v_pk_mul_f32 v[98:99], v[148:149], v[98:99]
	v_pk_mul_f32 v[100:101], v[148:149], v[100:101]
	v_pk_mul_f32 v[102:103], v[148:149], v[102:103]
	v_pk_add_f32 v[112:113], v[112:113], 1.0 op_sel_hi:[1,0]
	v_pk_add_f32 v[114:115], v[114:115], 1.0 op_sel_hi:[1,0]
	v_pk_add_f32 v[116:117], v[116:117], 1.0 op_sel_hi:[1,0]
	v_pk_add_f32 v[118:119], v[118:119], 1.0 op_sel_hi:[1,0]
	v_pk_add_f32 v[212:213], v[212:213], 1.0 op_sel_hi:[1,0]
	v_pk_add_f32 v[214:215], v[214:215], 1.0 op_sel_hi:[1,0]
	v_pk_add_f32 v[216:217], v[216:217], 1.0 op_sel_hi:[1,0]
	v_pk_add_f32 v[218:219], v[218:219], 1.0 op_sel_hi:[1,0]
	v_pk_mul_f32 v[104:105], v[104:105], v[112:113]
	v_pk_mul_f32 v[106:107], v[106:107], v[114:115]
	v_pk_mul_f32 v[108:109], v[108:109], v[116:117]
	v_pk_mul_f32 v[110:111], v[110:111], v[118:119]
	v_pk_mul_f32 v[120:121], v[120:121], v[212:213]
	v_pk_mul_f32 v[122:123], v[122:123], v[214:215]
	v_pk_mul_f32 v[124:125], v[124:125], v[216:217]
	v_pk_mul_f32 v[126:127], v[126:127], v[218:219]
	v_rcp_f32_e32 v120, v120
	v_rcp_f32_e32 v121, v121
	v_rcp_f32_e32 v122, v122
	v_rcp_f32_e32 v123, v123
	v_rcp_f32_e32 v124, v124
	v_rcp_f32_e32 v125, v125
	v_rcp_f32_e32 v126, v126
	v_rcp_f32_e32 v127, v127
	s_nop 0
	s_waitcnt vmcnt(8)
; __device__ __forceinline__ unsigned pk2(float lo, float hi) { unsigned r; asm("v_cvt_pk_bf16_f32 %0, %1, %2" : "=v"(r) : "v"(lo), "v"(hi)); return r; }
;     __device__ __forceinline__ void operator()(const f32x4 (&acc)[2][2][4][2], const pg8::Unit& u, int wr, int wc, int fr, int fq) const {
;     ...
;                 for (int m = 0; m < 4; ++m) {
;                     const size_t off = (size_t)(row0 + ai * 128 + m * 16) * DM + col0 + bj * 128;
;                     const u32x4 r = rr[m];
;                     f32x4 h0 = (f32x4){bf2f(r.x & 0xffffu), __builtin_bit_cast(float, r.x & 0xffff0000u), bf2f(r.y & 0xffffu), __builtin_bit_cast(float, r.y & 0xffff0000u)};
;                     f32x4 h1 = (f32x4){bf2f(r.z & 0xffffu), __builtin_bit_cast(float, r.z & 0xffff0000u), bf2f(r.w & 0xffffu), __builtin_bit_cast(float, r.w & 0xffff0000u)};
;                     h0 = h0 * i0 + g0 * acc[ai][bj][m][0]; h1 = h1 * i1 + g1 * acc[ai][bj][m][1];
;                     sq[ai][m] += ((h0[0] * h0[0] + h0[1] * h0[1]) + (h0[2] * h0[2] + h0[3] * h0[3])) + ((h1[0] * h1[0] + h1[1] * h1[1]) + (h1[2] * h1[2] + h1[3] * h1[3]));
;                     asm volatile("" : "+v"(sq[ai][m]));
;                     const f32x4 u0 = h0 * s0, u1 = h1 * s1;
;                     u32x4 w; w.x = pk2(u0[0], u0[1]); w.y = pk2(u0[2], u0[3]); w.z = pk2(u1[0], u1[1]); w.w = pk2(u1[2], u1[3]);
;                     *(u32x4*)(Un + off) = w;
	v_lshlrev_b32_e32 v188, 16, v236
	v_and_b32_e32 v189, 0xffff0000, v236
	v_lshlrev_b32_e32 v190, 16, v237
	v_and_b32_e32 v191, 0xffff0000, v237
	v_lshlrev_b32_e32 v192, 16, v238
	v_and_b32_e32 v193, 0xffff0000, v238
	v_lshlrev_b32_e32 v194, 16, v239
	v_and_b32_e32 v195, 0xffff0000, v239
	v_pk_mul_f32 v[188:189], v[120:121], v[188:189]
	v_pk_mul_f32 v[190:191], v[122:123], v[190:191]
	v_pk_mul_f32 v[192:193], v[124:125], v[192:193]
	v_pk_mul_f32 v[194:195], v[126:127], v[194:195]
	v_pk_fma_f32 v[188:189], v[60:61], v[96:97], v[188:189]
	v_pk_fma_f32 v[190:191], v[62:63], v[98:99], v[190:191]
	v_pk_fma_f32 v[192:193], v[56:57], v[100:101], v[192:193]
	v_pk_fma_f32 v[194:195], v[58:59], v[102:103], v[194:195]
	v_mul_f32_e32 v222, v189, v189
	v_mul_f32_e32 v223, v191, v191
	v_fmac_f32_e32 v222, v188, v188
	v_fmac_f32_e32 v223, v190, v190
	v_add_f32_e32 v222, v222, v223
	v_mul_f32_e32 v223, v193, v193
	v_mul_f32_e32 v228, v195, v195
	v_fmac_f32_e32 v223, v192, v192
	v_fmac_f32_e32 v228, v194, v194
	v_add_f32_e32 v223, v223, v228
	v_add_f32_e32 v222, v222, v223
	v_add_f32_e32 v164, v164, v222
	v_pk_mul_f32 v[188:189], v[104:105], v[188:189]
	v_pk_mul_f32 v[190:191], v[106:107], v[190:191]
	v_pk_mul_f32 v[192:193], v[108:109], v[192:193]
	v_pk_mul_f32 v[194:195], v[110:111], v[194:195]
	v_cvt_pk_bf16_f32 v236, v188, v189
	v_cvt_pk_bf16_f32 v237, v190, v191
	v_cvt_pk_bf16_f32 v238, v192, v193
	v_cvt_pk_bf16_f32 v239, v194, v195
	global_store_dwordx4 v155, v[236:239], s[0:1] offset:256
	v_lshlrev_b32_e32 v188, 16, v240
	v_and_b32_e32 v189, 0xffff0000, v240
	v_lshlrev_b32_e32 v190, 16, v241
	v_and_b32_e32 v191, 0xffff0000, v241
	v_lshlrev_b32_e32 v192, 16, v242
	v_and_b32_e32 v193, 0xffff0000, v242
	v_lshlrev_b32_e32 v194, 16, v243
	v_and_b32_e32 v195, 0xffff0000, v243
	v_pk_mul_f32 v[188:189], v[120:121], v[188:189]
	v_pk_mul_f32 v[190:191], v[122:123], v[190:191]
	v_pk_mul_f32 v[192:193], v[124:125], v[192:193]
	v_pk_mul_f32 v[194:195], v[126:127], v[194:195]
	v_pk_fma_f32 v[188:189], v[52:53], v[96:97], v[188:189]
	v_pk_fma_f32 v[190:191], v[54:55], v[98:99], v[190:191]
	v_pk_fma_f32 v[192:193], v[48:49], v[100:101], v[192:193]
	v_pk_fma_f32 v[194:195], v[50:51], v[102:103], v[194:195]
	v_mul_f32_e32 v222, v189, v189
	v_mul_f32_e32 v223, v191, v191
	v_fmac_f32_e32 v222, v188, v188
	v_fmac_f32_e32 v223, v190, v190
	v_add_f32_e32 v222, v222, v223
	v_mul_f32_e32 v223, v193, v193
	v_mul_f32_e32 v228, v195, v195
	v_fmac_f32_e32 v223, v192, v192
	v_fmac_f32_e32 v228, v194, v194
	v_add_f32_e32 v223, v223, v228
	v_add_f32_e32 v222, v222, v223
	v_add_f32_e32 v165, v165, v222
	v_pk_mul_f32 v[188:189], v[104:105], v[188:189]
	v_pk_mul_f32 v[190:191], v[106:107], v[190:191]
	v_pk_mul_f32 v[192:193], v[108:109], v[192:193]
	v_pk_mul_f32 v[194:195], v[110:111], v[194:195]
	v_cvt_pk_bf16_f32 v240, v188, v189
	v_cvt_pk_bf16_f32 v241, v190, v191
	v_cvt_pk_bf16_f32 v242, v192, v193
	v_cvt_pk_bf16_f32 v243, v194, v195
	global_store_dwordx4 v156, v[240:243], s[0:1] offset:256
	v_lshlrev_b32_e32 v188, 16, v204
	v_and_b32_e32 v189, 0xffff0000, v204
	v_lshlrev_b32_e32 v190, 16, v205
	v_and_b32_e32 v191, 0xffff0000, v205
	v_lshlrev_b32_e32 v192, 16, v206
	v_and_b32_e32 v193, 0xffff0000, v206
	v_lshlrev_b32_e32 v194, 16, v207
	v_and_b32_e32 v195, 0xffff0000, v207
	v_pk_mul_f32 v[188:189], v[120:121], v[188:189]
	v_pk_mul_f32 v[190:191], v[122:123], v[190:191]
	v_pk_mul_f32 v[192:193], v[124:125], v[192:193]
	v_pk_mul_f32 v[194:195], v[126:127], v[194:195]
	v_pk_fma_f32 v[188:189], v[44:45], v[96:97], v[188:189]
	v_pk_fma_f32 v[190:191], v[46:47], v[98:99], v[190:191]
	v_pk_fma_f32 v[192:193], v[40:41], v[100:101], v[192:193]
	v_pk_fma_f32 v[194:195], v[42:43], v[102:103], v[194:195]
	v_mul_f32_e32 v222, v189, v189
	v_mul_f32_e32 v223, v191, v191
	v_fmac_f32_e32 v222, v188, v188
	v_fmac_f32_e32 v223, v190, v190
	v_add_f32_e32 v222, v222, v223
	v_mul_f32_e32 v223, v193, v193
	v_mul_f32_e32 v228, v195, v195
	v_fmac_f32_e32 v223, v192, v192
	v_fmac_f32_e32 v228, v194, v194
	v_add_f32_e32 v223, v223, v228
	v_add_f32_e32 v222, v222, v223
	v_add_f32_e32 v166, v166, v222
	v_pk_mul_f32 v[188:189], v[104:105], v[188:189]
	v_pk_mul_f32 v[190:191], v[106:107], v[190:191]
	v_pk_mul_f32 v[192:193], v[108:109], v[192:193]
	v_pk_mul_f32 v[194:195], v[110:111], v[194:195]
	v_cvt_pk_bf16_f32 v204, v188, v189
	v_cvt_pk_bf16_f32 v205, v190, v191
	v_cvt_pk_bf16_f32 v206, v192, v193
	v_cvt_pk_bf16_f32 v207, v194, v195
	global_store_dwordx4 v157, v[204:207], s[0:1] offset:256
	v_lshlrev_b32_e32 v188, 16, v208
	v_and_b32_e32 v189, 0xffff0000, v208
	v_lshlrev_b32_e32 v190, 16, v209
	v_and_b32_e32 v191, 0xffff0000, v209
	v_lshlrev_b32_e32 v192, 16, v210
	v_and_b32_e32 v193, 0xffff0000, v210
	v_lshlrev_b32_e32 v194, 16, v211
	v_and_b32_e32 v195, 0xffff0000, v211
	v_pk_mul_f32 v[188:189], v[120:121], v[188:189]
	v_pk_mul_f32 v[190:191], v[122:123], v[190:191]
	v_pk_mul_f32 v[192:193], v[124:125], v[192:193]
	v_pk_mul_f32 v[194:195], v[126:127], v[194:195]
	v_pk_fma_f32 v[188:189], v[36:37], v[96:97], v[188:189]
	v_pk_fma_f32 v[190:191], v[38:39], v[98:99], v[190:191]
	v_pk_fma_f32 v[192:193], v[32:33], v[100:101], v[192:193]
	v_pk_fma_f32 v[194:195], v[34:35], v[102:103], v[194:195]
	v_mul_f32_e32 v222, v189, v189
	v_mul_f32_e32 v223, v191, v191
	v_fmac_f32_e32 v222, v188, v188
	v_fmac_f32_e32 v223, v190, v190
	v_add_f32_e32 v222, v222, v223
	v_mul_f32_e32 v223, v193, v193
	v_mul_f32_e32 v228, v195, v195
	v_fmac_f32_e32 v223, v192, v192
	v_fmac_f32_e32 v228, v194, v194
	v_add_f32_e32 v223, v223, v228
	v_add_f32_e32 v222, v222, v223
	v_add_f32_e32 v167, v167, v222
	v_pk_mul_f32 v[188:189], v[104:105], v[188:189]
	v_pk_mul_f32 v[190:191], v[106:107], v[190:191]
	v_pk_mul_f32 v[192:193], v[108:109], v[192:193]
	v_pk_mul_f32 v[194:195], v[110:111], v[194:195]
	v_cvt_pk_bf16_f32 v208, v188, v189
	v_cvt_pk_bf16_f32 v209, v190, v191
	v_cvt_pk_bf16_f32 v210, v192, v193
	v_cvt_pk_bf16_f32 v211, v194, v195
	global_store_dwordx4 v158, v[208:211], s[0:1] offset:256
	s_waitcnt vmcnt(4)
; __device__ __forceinline__ unsigned pk2(float lo, float hi) { unsigned r; asm("v_cvt_pk_bf16_f32 %0, %1, %2" : "=v"(r) : "v"(lo), "v"(hi)); return r; }
; __device__ __forceinline__ float shx(float v, int m, int lane) { return __builtin_bit_cast(float, __builtin_amdgcn_ds_bpermute((lane ^ m) << 2, __builtin_bit_cast(int, v))); }
;     __device__ __forceinline__ void operator()(const f32x4 (&acc)[2][2][4][2], const pg8::Unit& u, int wr, int wc, int fr, int fq) const {
;     ...
;                 for (int m = 0; m < 4; ++m) {
;                     const size_t off = (size_t)(row0 + ai * 128 + m * 16) * DM + col0 + bj * 128;
;                     const u32x4 r = rr[m];
;                     f32x4 h0 = (f32x4){bf2f(r.x & 0xffffu), __builtin_bit_cast(float, r.x & 0xffff0000u), bf2f(r.y & 0xffffu), __builtin_bit_cast(float, r.y & 0xffff0000u)};
;                     f32x4 h1 = (f32x4){bf2f(r.z & 0xffffu), __builtin_bit_cast(float, r.z & 0xffff0000u), bf2f(r.w & 0xffffu), __builtin_bit_cast(float, r.w & 0xffff0000u)};
;                     h0 = h0 * i0 + g0 * acc[ai][bj][m][0]; h1 = h1 * i1 + g1 * acc[ai][bj][m][1];
;                     sq[ai][m] += ((h0[0] * h0[0] + h0[1] * h0[1]) + (h0[2] * h0[2] + h0[3] * h0[3])) + ((h1[0] * h1[0] + h1[1] * h1[1]) + (h1[2] * h1[2] + h1[3] * h1[3]));
;                     asm volatile("" : "+v"(sq[ai][m]));
;                     const f32x4 u0 = h0 * s0, u1 = h1 * s1;
;                     u32x4 w; w.x = pk2(u0[0], u0[1]); w.y = pk2(u0[2], u0[3]); w.z = pk2(u1[0], u1[1]); w.w = pk2(u1[2], u1[3]);
;                     *(u32x4*)(Un + off) = w;
;                 }
;                 __builtin_amdgcn_sched_barrier(0);
;             }
;         }
;         if (Un) {
; #pragma unroll
;             for (int ai = 0; ai < 2; ++ai)
; #pragma unroll
;                 for (int m = 0; m < 4; ++m) { float t = sq[ai][m]; t += shx(t, 16, fq * 16 + fr); t += shx(t, 32, fq * 16 + fr);
;                     if (fq == 0) ssn[(size_t)(row0 + ai * 128 + m * 16) * 16 + u.pn * 4 + wc] = t; }
	v_lshlrev_b32_e32 v188, 16, v244
	v_and_b32_e32 v189, 0xffff0000, v244
	v_lshlrev_b32_e32 v190, 16, v245
	v_and_b32_e32 v191, 0xffff0000, v245
	v_lshlrev_b32_e32 v192, 16, v246
	v_and_b32_e32 v193, 0xffff0000, v246
	v_lshlrev_b32_e32 v194, 16, v247
	v_and_b32_e32 v195, 0xffff0000, v247
	v_pk_mul_f32 v[188:189], v[120:121], v[188:189]
	v_pk_mul_f32 v[190:191], v[122:123], v[190:191]
	v_pk_mul_f32 v[192:193], v[124:125], v[192:193]
	v_pk_mul_f32 v[194:195], v[126:127], v[194:195]
	v_pk_fma_f32 v[188:189], v[28:29], v[96:97], v[188:189]
	v_pk_fma_f32 v[190:191], v[30:31], v[98:99], v[190:191]
	v_pk_fma_f32 v[192:193], v[24:25], v[100:101], v[192:193]
	v_pk_fma_f32 v[194:195], v[26:27], v[102:103], v[194:195]
	v_mul_f32_e32 v222, v189, v189
	v_mul_f32_e32 v223, v191, v191
	v_fmac_f32_e32 v222, v188, v188
	v_fmac_f32_e32 v223, v190, v190
	v_add_f32_e32 v222, v222, v223
	v_mul_f32_e32 v223, v193, v193
	v_mul_f32_e32 v228, v195, v195
	v_fmac_f32_e32 v223, v192, v192
	v_fmac_f32_e32 v228, v194, v194
	v_add_f32_e32 v223, v223, v228
	v_add_f32_e32 v222, v222, v223
	v_add_f32_e32 v168, v168, v222
	v_pk_mul_f32 v[188:189], v[104:105], v[188:189]
	v_pk_mul_f32 v[190:191], v[106:107], v[190:191]
	v_pk_mul_f32 v[192:193], v[108:109], v[192:193]
	v_pk_mul_f32 v[194:195], v[110:111], v[194:195]
	v_cvt_pk_bf16_f32 v244, v188, v189
	v_cvt_pk_bf16_f32 v245, v190, v191
	v_cvt_pk_bf16_f32 v246, v192, v193
	v_cvt_pk_bf16_f32 v247, v194, v195
	global_store_dwordx4 v159, v[244:247], s[0:1] offset:256
	v_lshlrev_b32_e32 v188, 16, v248
	v_and_b32_e32 v189, 0xffff0000, v248
	v_lshlrev_b32_e32 v190, 16, v249
	v_and_b32_e32 v191, 0xffff0000, v249
	v_lshlrev_b32_e32 v192, 16, v250
	v_and_b32_e32 v193, 0xffff0000, v250
	v_lshlrev_b32_e32 v194, 16, v251
	v_and_b32_e32 v195, 0xffff0000, v251
	v_pk_mul_f32 v[188:189], v[120:121], v[188:189]
	v_pk_mul_f32 v[190:191], v[122:123], v[190:191]
	v_pk_mul_f32 v[192:193], v[124:125], v[192:193]
	v_pk_mul_f32 v[194:195], v[126:127], v[194:195]
	v_pk_fma_f32 v[188:189], v[20:21], v[96:97], v[188:189]
	v_pk_fma_f32 v[190:191], v[22:23], v[98:99], v[190:191]
	v_pk_fma_f32 v[192:193], v[16:17], v[100:101], v[192:193]
	v_pk_fma_f32 v[194:195], v[18:19], v[102:103], v[194:195]
	v_mul_f32_e32 v222, v189, v189
	v_mul_f32_e32 v223, v191, v191
	v_fmac_f32_e32 v222, v188, v188
	v_fmac_f32_e32 v223, v190, v190
	v_add_f32_e32 v222, v222, v223
	v_mul_f32_e32 v223, v193, v193
	v_mul_f32_e32 v228, v195, v195
	v_fmac_f32_e32 v223, v192, v192
	v_fmac_f32_e32 v228, v194, v194
	v_add_f32_e32 v223, v223, v228
	v_add_f32_e32 v222, v222, v223
	v_add_f32_e32 v169, v169, v222
	v_pk_mul_f32 v[188:189], v[104:105], v[188:189]
	v_pk_mul_f32 v[190:191], v[106:107], v[190:191]
	v_pk_mul_f32 v[192:193], v[108:109], v[192:193]
	v_pk_mul_f32 v[194:195], v[110:111], v[194:195]
	v_cvt_pk_bf16_f32 v248, v188, v189
	v_cvt_pk_bf16_f32 v249, v190, v191
	v_cvt_pk_bf16_f32 v250, v192, v193
	v_cvt_pk_bf16_f32 v251, v194, v195
	global_store_dwordx4 v160, v[248:251], s[0:1] offset:256
	v_lshlrev_b32_e32 v188, 16, v128
	v_and_b32_e32 v189, 0xffff0000, v128
	v_lshlrev_b32_e32 v190, 16, v129
	v_and_b32_e32 v191, 0xffff0000, v129
	v_lshlrev_b32_e32 v192, 16, v130
	v_and_b32_e32 v193, 0xffff0000, v130
	v_lshlrev_b32_e32 v194, 16, v131
	v_and_b32_e32 v195, 0xffff0000, v131
	v_pk_mul_f32 v[188:189], v[120:121], v[188:189]
	v_pk_mul_f32 v[190:191], v[122:123], v[190:191]
	v_pk_mul_f32 v[192:193], v[124:125], v[192:193]
	v_pk_mul_f32 v[194:195], v[126:127], v[194:195]
	v_pk_fma_f32 v[188:189], v[12:13], v[96:97], v[188:189]
	v_pk_fma_f32 v[190:191], v[14:15], v[98:99], v[190:191]
	v_pk_fma_f32 v[192:193], v[8:9], v[100:101], v[192:193]
	v_pk_fma_f32 v[194:195], v[10:11], v[102:103], v[194:195]
	v_mul_f32_e32 v222, v189, v189
	v_mul_f32_e32 v223, v191, v191
	v_fmac_f32_e32 v222, v188, v188
	v_fmac_f32_e32 v223, v190, v190
	v_add_f32_e32 v222, v222, v223
	v_mul_f32_e32 v223, v193, v193
	v_mul_f32_e32 v228, v195, v195
	v_fmac_f32_e32 v223, v192, v192
	v_fmac_f32_e32 v228, v194, v194
	v_add_f32_e32 v223, v223, v228
	v_add_f32_e32 v222, v222, v223
	v_add_f32_e32 v170, v170, v222
	v_pk_mul_f32 v[188:189], v[104:105], v[188:189]
	v_pk_mul_f32 v[190:191], v[106:107], v[190:191]
	v_pk_mul_f32 v[192:193], v[108:109], v[192:193]
	v_pk_mul_f32 v[194:195], v[110:111], v[194:195]
	v_cvt_pk_bf16_f32 v128, v188, v189
	v_cvt_pk_bf16_f32 v129, v190, v191
	v_cvt_pk_bf16_f32 v130, v192, v193
	v_cvt_pk_bf16_f32 v131, v194, v195
	global_store_dwordx4 v161, v[128:131], s[0:1] offset:256
	v_lshlrev_b32_e32 v188, 16, v132
	v_and_b32_e32 v189, 0xffff0000, v132
	v_lshlrev_b32_e32 v190, 16, v133
	v_and_b32_e32 v191, 0xffff0000, v133
	v_lshlrev_b32_e32 v192, 16, v134
	v_and_b32_e32 v193, 0xffff0000, v134
	v_lshlrev_b32_e32 v194, 16, v135
	v_and_b32_e32 v195, 0xffff0000, v135
	v_pk_mul_f32 v[188:189], v[120:121], v[188:189]
	v_pk_mul_f32 v[190:191], v[122:123], v[190:191]
	v_pk_mul_f32 v[192:193], v[124:125], v[192:193]
	v_pk_mul_f32 v[194:195], v[126:127], v[194:195]
	v_pk_fma_f32 v[188:189], v[4:5], v[96:97], v[188:189]
	v_pk_fma_f32 v[190:191], v[6:7], v[98:99], v[190:191]
	v_pk_fma_f32 v[192:193], v[0:1], v[100:101], v[192:193]
	v_pk_fma_f32 v[194:195], v[2:3], v[102:103], v[194:195]
	v_mul_f32_e32 v222, v189, v189
	v_mul_f32_e32 v223, v191, v191
	v_fmac_f32_e32 v222, v188, v188
	v_fmac_f32_e32 v223, v190, v190
	v_add_f32_e32 v222, v222, v223
	v_mul_f32_e32 v223, v193, v193
	v_mul_f32_e32 v228, v195, v195
	v_fmac_f32_e32 v223, v192, v192
	v_fmac_f32_e32 v228, v194, v194
	v_add_f32_e32 v223, v223, v228
	v_add_f32_e32 v222, v222, v223
	v_add_f32_e32 v171, v171, v222
	v_pk_mul_f32 v[188:189], v[104:105], v[188:189]
	v_pk_mul_f32 v[190:191], v[106:107], v[190:191]
	v_pk_mul_f32 v[192:193], v[108:109], v[192:193]
	v_pk_mul_f32 v[194:195], v[110:111], v[194:195]
	v_cvt_pk_bf16_f32 v132, v188, v189
	v_cvt_pk_bf16_f32 v133, v190, v191
	v_cvt_pk_bf16_f32 v134, v192, v193
	v_cvt_pk_bf16_f32 v135, v194, v195
	global_store_dwordx4 v162, v[132:135], s[0:1] offset:256
	v_lshlrev_b32_e32 v222, 2, v234
	v_lshl_add_u32 v223, v235, 6, v222
	v_xor_b32_e32 v222, 64, v223
	v_xor_b32_e32 v223, 0x80, v223
	ds_bpermute_b32 v188, v222, v164
	ds_bpermute_b32 v189, v222, v165
	ds_bpermute_b32 v190, v222, v166
	ds_bpermute_b32 v191, v222, v167
	ds_bpermute_b32 v192, v222, v168
	ds_bpermute_b32 v193, v222, v169
	ds_bpermute_b32 v194, v222, v170
	ds_bpermute_b32 v195, v222, v171
	s_lshl_b32 s24, s46, 4
	s_add_u32 s24, s57, s24
	s_addc_u32 s25, s59, 0
	v_lshlrev_b32_e32 v204, 6, v163
	v_add_u32_e32 v205, 0x400, v204
	v_add_u32_e32 v206, 0x800, v204
	v_add_u32_e32 v207, 0xc00, v204
	v_add_u32_e32 v208, 0x2000, v204
	v_add_u32_e32 v209, 0x2400, v204
	v_add_u32_e32 v210, 0x2800, v204
	v_add_u32_e32 v211, 0x2c00, v204
	s_waitcnt lgkmcnt(0)
; __device__ __forceinline__ float shx(float v, int m, int lane) { return __builtin_bit_cast(float, __builtin_amdgcn_ds_bpermute((lane ^ m) << 2, __builtin_bit_cast(int, v))); }
;     __device__ __forceinline__ void operator()(const f32x4 (&acc)[2][2][4][2], const pg8::Unit& u, int wr, int wc, int fr, int fq) const {
;     ...
;         if (Un) {
; #pragma unroll
;             for (int ai = 0; ai < 2; ++ai)
; #pragma unroll
;                 for (int m = 0; m < 4; ++m) { float t = sq[ai][m]; t += shx(t, 16, fq * 16 + fr); t += shx(t, 32, fq * 16 + fr);
;                     if (fq == 0) ssn[(size_t)(row0 + ai * 128 + m * 16) * 16 + u.pn * 4 + wc] = t; }
;         }
	v_add_f32_e32 v164, v164, v188
	v_add_f32_e32 v165, v165, v189
	v_add_f32_e32 v166, v166, v190
	v_add_f32_e32 v167, v167, v191
	v_add_f32_e32 v168, v168, v192
	v_add_f32_e32 v169, v169, v193
	v_add_f32_e32 v170, v170, v194
	v_add_f32_e32 v171, v171, v195
	ds_bpermute_b32 v188, v223, v164
	ds_bpermute_b32 v189, v223, v165
	ds_bpermute_b32 v190, v223, v166
	ds_bpermute_b32 v191, v223, v167
	ds_bpermute_b32 v192, v223, v168
	ds_bpermute_b32 v193, v223, v169
	ds_bpermute_b32 v194, v223, v170
	ds_bpermute_b32 v195, v223, v171
	v_cmp_eq_u32_e32 vcc, 0, v235
	s_waitcnt lgkmcnt(0)
	v_add_f32_e32 v164, v164, v188
	v_add_f32_e32 v165, v165, v189
	v_add_f32_e32 v166, v166, v190
	v_add_f32_e32 v167, v167, v191
	v_add_f32_e32 v168, v168, v192
	v_add_f32_e32 v169, v169, v193
	v_add_f32_e32 v170, v170, v194
	v_add_f32_e32 v171, v171, v195
	s_and_saveexec_b64 s[26:27], vcc
	global_store_dword v204, v164, s[24:25]
	global_store_dword v205, v165, s[24:25]
	global_store_dword v206, v166, s[24:25]
	global_store_dword v207, v167, s[24:25]
	global_store_dword v208, v168, s[24:25]
	global_store_dword v209, v169, s[24:25]
	global_store_dword v210, v170, s[24:25]
	global_store_dword v211, v171, s[24:25]
	s_or_b64 exec, exec, s[26:27]
